# attention items: one static s_setprio 1 for the younger half of the waves (4-7) before the pair loop, reset at item end
# baseline (speedup 1.0000x reference)
; __device__ __forceinline__ int fresh_tid() { int t; asm volatile("v_mov_b32 %0, %1" : "=v"(t) : "v"(threadIdx.x)); return t; }
; template <int TYPE>
; __device__ __forceinline__ void attn_item(const Ctx& a, int b, int h, int qt, LAS unsigned char* lds) {
;     ...
;     const int tid = fresh_tid(), lane = tid & 63, wv = tid >> 6, l32 = lane & 31, hb = lane >> 5;
;     const bf16_t* mr = (const bf16_t*)(a.ws + B_MLA); const bf16_t* pa = (const bf16_t*)(a.ws + B_PROJ); const bf16_t* kro = (const bf16_t*)(a.ws + B_KROPE);
;     bf16_t* br = (bf16_t*)(a.ws + B_BRANCH);
;     const int qrow = qt * 256 + wv * 32 + l32;
;     bf16x8 Q[NKK];
;     {
;         const bf16_t* qp = TYPE == 0 ? mr + (size_t)qrow * MR + h * 96 : pa + (size_t)qrow * PA + C_MQ + h * 64;
; #pragma unroll
;         for (int kk = 0; kk < NKK; ++kk) Q[kk] = *(const bf16x8*)(qp + kk * 16 + hb * 8);
;     }
;     unsigned qmask = 0xffffffffu;
;     if (TYPE == 1) qmask = ((const unsigned*)(a.ws + WS_MASK))[(size_t)h * SEQ + qrow];
;     f32x16 oacc[2];
; #pragma unroll
;     for (int db = 0; db < 2; ++db)
; #pragma unroll
;         for (int r = 0; r < 16; ++r) oacc[db][r] = 0.f;
;     float mrun = 0.f, lrun = 0.f;
;     const int npair = (qt + 1) * 2;
;     u32x4 kreg[NKC], vreg[2];
;     ...
;     AT_LOAD(0); AT_STORE(0);
;     __syncthreads();
.Lat0_entry:
	s_lshr_b32 s47, s12, 4
	s_sub_u32 s47, 31, s47
	s_and_b32 s50, s12, 7
	v_lshrrev_b32 v1, 6, v179
	s_add_u32 s30, s47, 1
	s_lshl_b32 s30, s30, 1
	v_readfirstlane_b32 s51, v1
	v_and_b32 v14, 31, v195
	v_lshrrev_b32 v15, 5, v195
	s_lshl_b32 s8, s47, 8
	s_lshl_b32 s9, s51, 5
	s_add_u32 s8, s8, s9
	v_add_u32 v144, s8, v14
	v_add_u32 v208, s9, v14
	v_lshlrev_b32 v181, 2, v15
	v_sub_u32 v208, v208, v181
	s_mul_i32 s9, s50, 0xc0
	s_add_u32 s56, s16, 0xc8f4200
	s_addc_u32 s57, s17, 0
	s_add_u32 s56, s56, s9
	s_addc_u32 s57, s57, 0
	s_movk_i32 s8, 0xe00
	v_mul_lo_u32 v181, v144, s8
	v_lshl_add_u32 v181, v15, 4, v181
	global_load_dwordx4 v[112:115], v181, s[56:57] offset:0
	global_load_dwordx4 v[116:119], v181, s[56:57] offset:32
	global_load_dwordx4 v[120:123], v181, s[56:57] offset:64
	global_load_dwordx4 v[124:127], v181, s[56:57] offset:96
	global_load_dwordx4 v[128:131], v181, s[56:57] offset:128
	global_load_dwordx4 v[132:135], v181, s[56:57] offset:160
	v_lshrrev_b32 v181, 3, v179
	v_and_b32 v212, 7, v179
	s_lshl_b32 s9, s50, 8
	s_add_u32 s52, s16, 0xc8f4800
	s_addc_u32 s53, s17, 0
	s_add_u32 s52, s52, s9
	s_addc_u32 s53, s53, 0
	s_lshl_b32 s9, s50, 6
	s_add_u32 s54, s16, 0xe4f4200
	s_addc_u32 s55, s17, 0
	s_add_u32 s54, s54, s9
	s_addc_u32 s55, s55, 0
	v_mul_u32_u24 v184, 0xe00, v181
	v_lshl_add_u32 v184, v212, 4, v184
	v_add_u32 v185, 0x38000, v184
	v_lshrrev_b32 v1, 2, v179
	v_and_b32 v188, 3, v179
	v_lshlrev_b32 v186, 9, v1
	v_lshl_add_u32 v186, v188, 4, v186
	v_mul_u32_u24 v201, 0xd0, v1
	v_lshl_add_u32 v201, v188, 4, v201
	v_add_u32 v201, 0x80, v201
	v_mul_u32_u24 v190, 208, v14
	v_lshl_add_u32 v190, v15, 4, v190
	v_mul_u32_u24 v193, 208, v181
	v_lshl_add_u32 v193, v212, 4, v193
	v_and_b32 v1, 2, v181
	v_lshlrev_b32 v1, 5, v1
	v_lshlrev_b32 v188, 4, v212
	v_xor_b32 v1, v1, v188
	v_lshl_add_u32 v200, v181, 7, v1
	v_add_u32 v200, 26624, v200
	v_bfe_u32 v1, v195, 2, 2
	v_lshlrev_b32 v191, 7, v1
	v_bfe_u32 v1, v195, 3, 1
	v_lshl_add_u32 v191, v1, 6, v191
	v_bfe_u32 v1, v195, 4, 1
	v_lshl_add_u32 v191, v1, 5, v191
	v_and_b32 v1, 3, v195
	v_lshl_add_u32 v191, v1, 3, v191
	v_lshl_add_u32 v191, v15, 9, v191
	v_add_u32 v191, 26624, v191
	v_xor_b32 v192, 64, v191
	global_load_dwordx4 v[2:5], v184, s[52:53]
	global_load_dwordx4 v[6:9], v184, s[52:53] offset:128
	global_load_dwordx4 v[10:13], v185, s[52:53]
	global_load_dwordx4 v[136:139], v185, s[52:53] offset:128
	global_load_dwordx4 v[140:143], v186, s[54:55]
	s_add_u32 s52, s52, 0x70000
	s_addc_u32 s53, s53, 0
	s_add_u32 s54, s54, 0x10000
	s_addc_u32 s55, s55, 0
	v_mov_b32 v16, 0
	v_mov_b32 v17, 0
	v_mov_b32 v18, 0
	v_mov_b32 v19, 0
	v_mov_b32 v20, 0
	v_mov_b32 v21, 0
	v_mov_b32 v22, 0
	v_mov_b32 v23, 0
	v_mov_b32 v24, 0
	v_mov_b32 v25, 0
	v_mov_b32 v26, 0
	v_mov_b32 v27, 0
	v_mov_b32 v28, 0
	v_mov_b32 v29, 0
	v_mov_b32 v30, 0
	v_mov_b32 v31, 0
	v_mov_b32 v32, 0
	v_mov_b32 v33, 0
	v_mov_b32 v34, 0
	v_mov_b32 v35, 0
	v_mov_b32 v36, 0
	v_mov_b32 v37, 0
	v_mov_b32 v38, 0
	v_mov_b32 v39, 0
	v_mov_b32 v40, 0
	v_mov_b32 v41, 0
	v_mov_b32 v42, 0
	v_mov_b32 v43, 0
	v_mov_b32 v44, 0
	v_mov_b32 v45, 0
	v_mov_b32 v46, 0
	v_mov_b32 v47, 0
	v_mov_b32 v205, 0
	v_mov_b32 v206, 0
	v_mov_b32 v207, 0x41000000
	s_mov_b64 s[36:37], 0
	s_mov_b32 s26, 0
	s_waitcnt vmcnt(0)
	ds_write_b128 v193, v[2:5]
	ds_write_b128 v193, v[10:13] offset:13312
	ds_write_b128 v200, v[6:9]
	ds_write_b128 v200, v[136:139] offset:8192
	ds_write_b128 v201, v[140:143]
	s_waitcnt lgkmcnt(0)
	global_load_dwordx4 v[2:5], v184, s[52:53]
	global_load_dwordx4 v[6:9], v184, s[52:53] offset:128
	global_load_dwordx4 v[10:13], v185, s[52:53]
	global_load_dwordx4 v[136:139], v185, s[52:53] offset:128
	global_load_dwordx4 v[140:143], v186, s[54:55]
	s_add_u32 s52, s52, 0x70000
	s_addc_u32 s53, s53, 0
	s_add_u32 s54, s54, 0x10000
	s_addc_u32 s55, s55, 0
	s_mov_b32 s8, 0xa800
	v_add_u32 v193, s8, v193
	v_add_u32 v200, s8, v200
	v_add_u32 v201, s8, v201
	s_mov_b32 s12, 0
	s_mov_b32 s13, 1
	s_waitcnt lgkmcnt(0)
	s_barrier
	s_cmp_ge_u32 s51, 4
	s_cbranch_scc0 .Lat0_prio_done
	s_setprio 1
.Lat0_prio_done:
.Lat0_loop:
	s_add_u32 s8, s26, 2
	s_cmp_ge_u32 s8, s30
	s_cselect_b32 s57, 1, 0
	s_cmp_eq_u32 s57, 1
	s_cbranch_scc1 .Lat0_gen
	s_cmp_lg_u64 s[36:37], 0
	s_cbranch_scc1 .Lat0_gen
; template <int TYPE>
; __device__ __forceinline__ void attn_item(const Ctx& a, int b, int h, int qt, LAS unsigned char* lds) {
;     ...
;         for (int sub = 0; sub < 2; ++sub) {
;             const int kloc = kp * 2 + sub - qt * 4;
;             act[sub] = (kloc < 0) || (kloc * 64 <= wv * 32 + 31);
;             if (TYPE == 1 && kloc < 0) act[sub] = __builtin_amdgcn_ballot_w64((qmask >> ((kp * 2 + sub) >> 2)) & 1u) != 0ull;
; #pragma unroll
;             for (int kb = 0; kb < 2; ++kb)
; #pragma unroll
;                 for (int r = 0; r < 16; ++r) s[sub][kb][r] = -mref;
;         }
; #pragma unroll
;         for (int kk = 0; kk < NKK; ++kk)
; #pragma unroll
;             for (int sub = 0; sub < 2; ++sub)
;                 if (act[sub]) {
; #pragma unroll
;                     for (int kb = 0; kb < 2; ++kb) {
;                         bf16x8 ka = *(const LAS bf16x8*)(Kt + (sub * 64 + kb * 32 + l32) * KLD + kk * 16 + hb * 8);
;                         s[sub][kb] = __builtin_amdgcn_mfma_f32_32x32x16_bf16(ka, Q[kk], s[sub][kb], 0, 0, 0);
;                     }
;                 }
; #pragma unroll
;         for (int sub = 0; sub < 2; ++sub) {
;             if (!act[sub]) continue;
;             const int kt = kp * 2 + sub, kloc = kt - qt * 4;
;             if (kloc >= 0) {
; #pragma unroll
;                 for (int kb = 0; kb < 2; ++kb)
; #pragma unroll
;                     for (int r = 0; r < 16; ++r) { int kabs = kt * 64 + kb * 32 + (r >> 2) * 8 + hb * 4 + (r & 3); if (kabs > qrow) s[sub][kb][r] = -1e30f; }
;             } else if (TYPE == 1) {
;                 if (!((qmask >> (kt >> 2)) & 1u)) {
; #pragma unroll
;                     for (int kb = 0; kb < 2; ++kb)
; #pragma unroll
;                         for (int r = 0; r < 16; ++r) s[sub][kb][r] = -1e30f;
;                 }
;             }
;             float mx = -1e30f;
; #pragma unroll
;             for (int kb = 0; kb < 2; ++kb)
; #pragma unroll
;                 for (int r = 0; r < 16; ++r) mx = fmaxf(mx, s[sub][kb][r]);
;             mx = fmaxf(mx, __shfl_xor(mx, 32));
;             const float delta = mrun - mref;
;             const bool bump = (mx - delta) > 8.f;
;             const bool rare = __builtin_amdgcn_ballot_w64(bump || delta != 0.f) != 0ull;
;             float fpost = 1.f;
;             if (rare) {
;                 const float mnew = bump ? mref + mx : mrun;
	v_mov_b32 v211, v0
	ds_read_b128 v[146:149], v190 offset:0
	ds_read_b128 v[150:153], v190 offset:6656
	ds_read_b128 v[154:157], v190 offset:32
	ds_read_b128 v[158:161], v190 offset:6688
	ds_read_b128 v[162:165], v190 offset:64
	ds_read_b128 v[166:169], v190 offset:6720
	s_waitcnt lgkmcnt(5)
	v_mfma_f32_32x32x16_bf16 v[48:63], v[146:149], v[112:115], 0
	ds_read_b128 v[170:173], v190 offset:96
	s_waitcnt lgkmcnt(5)
	v_mfma_f32_32x32x16_bf16 v[64:79], v[150:153], v[112:115], 0
	ds_read_b128 v[174:177], v190 offset:6752
	s_waitcnt lgkmcnt(5)
	v_mfma_f32_32x32x16_bf16 v[48:63], v[154:157], v[116:119], v[48:63]
	ds_read_b128 v[146:149], v190 offset:128
	s_waitcnt lgkmcnt(5)
	v_mfma_f32_32x32x16_bf16 v[64:79], v[158:161], v[116:119], v[64:79]
	ds_read_b128 v[150:153], v190 offset:6784
	s_waitcnt lgkmcnt(5)
	v_mfma_f32_32x32x16_bf16 v[48:63], v[162:165], v[120:123], v[48:63]
	ds_read_b128 v[154:157], v190 offset:160
	s_waitcnt lgkmcnt(5)
	v_mfma_f32_32x32x16_bf16 v[64:79], v[166:169], v[120:123], v[64:79]
	ds_read_b128 v[158:161], v190 offset:6816
	s_waitcnt lgkmcnt(5)
	v_mfma_f32_32x32x16_bf16 v[48:63], v[170:173], v[124:127], v[48:63]
	ds_read_b128 v[162:165], v190 offset:13312
	s_waitcnt lgkmcnt(5)
	v_mfma_f32_32x32x16_bf16 v[64:79], v[174:177], v[124:127], v[64:79]
	ds_read_b128 v[166:169], v190 offset:19968
	s_waitcnt lgkmcnt(5)
	v_mfma_f32_32x32x16_bf16 v[48:63], v[146:149], v[128:131], v[48:63]
	ds_read_b128 v[170:173], v190 offset:13344
	s_waitcnt lgkmcnt(5)
	v_mfma_f32_32x32x16_bf16 v[64:79], v[150:153], v[128:131], v[64:79]
	ds_read_b128 v[174:177], v190 offset:20000
	s_waitcnt lgkmcnt(5)
	v_mfma_f32_32x32x16_bf16 v[48:63], v[154:157], v[132:135], v[48:63]
	ds_read_b128 v[146:149], v190 offset:13376
	s_waitcnt lgkmcnt(5)
	v_mfma_f32_32x32x16_bf16 v[64:79], v[158:161], v[132:135], v[64:79]
	ds_read_b128 v[150:153], v190 offset:20032
	s_waitcnt vmcnt(0)
	s_waitcnt lgkmcnt(5)
	v_mfma_f32_32x32x16_bf16 v[80:95], v[162:165], v[112:115], 0
	ds_read_b128 v[154:157], v190 offset:13408
	s_nop 3
	v_max3_f32 v211, v211, v48, v49
	v_exp_f32 v48, v48
	v_exp_f32 v49, v49
	v_max3_f32 v211, v211, v50, v51
	v_exp_f32 v50, v50
	v_exp_f32 v51, v51
	v_add_f32 v188, v48, v49
	v_cvt_pk_bf16_f32 v48, v48, v49
	s_waitcnt lgkmcnt(5)
	v_mfma_f32_32x32x16_bf16 v[96:111], v[166:169], v[112:115], 0
	ds_write_b128 v193, v[2:5]
	ds_read_b128 v[158:161], v190 offset:20064
	v_max3_f32 v211, v211, v52, v53
	v_exp_f32 v52, v52
	v_exp_f32 v53, v53
	v_add_f32 v188, v188, v50
	v_add_f32 v188, v188, v51
	v_cvt_pk_bf16_f32 v49, v50, v51
	v_max3_f32 v211, v211, v54, v55
	v_exp_f32 v54, v54
	s_waitcnt lgkmcnt(6)
	v_mfma_f32_32x32x16_bf16 v[80:95], v[170:173], v[116:119], v[80:95]
	ds_read_b128 v[162:165], v190 offset:13440
	v_exp_f32 v55, v55
	v_add_f32 v188, v188, v52
	v_add_f32 v188, v188, v53
	v_cvt_pk_bf16_f32 v50, v52, v53
	v_max3_f32 v211, v211, v56, v57
	v_exp_f32 v56, v56
	v_exp_f32 v57, v57
	v_add_f32 v188, v188, v54
	s_waitcnt lgkmcnt(6)
	v_mfma_f32_32x32x16_bf16 v[96:111], v[174:177], v[116:119], v[96:111]
	ds_write_b128 v193, v[10:13] offset:13312
	ds_read_b128 v[166:169], v190 offset:20096
	v_add_f32 v188, v188, v55
	v_cvt_pk_bf16_f32 v51, v54, v55
	v_max3_f32 v211, v211, v58, v59
	v_exp_f32 v58, v58
	v_exp_f32 v59, v59
	v_add_f32 v188, v188, v56
	v_add_f32 v188, v188, v57
	v_cvt_pk_bf16_f32 v52, v56, v57
	s_waitcnt lgkmcnt(7)
	v_mfma_f32_32x32x16_bf16 v[80:95], v[146:149], v[120:123], v[80:95]
	ds_read_b128 v[170:173], v190 offset:13472
	v_max3_f32 v211, v211, v60, v61
	v_exp_f32 v60, v60
	v_exp_f32 v61, v61
	v_add_f32 v188, v188, v58
	v_add_f32 v188, v188, v59
	v_cvt_pk_bf16_f32 v53, v58, v59
	v_max3_f32 v211, v211, v62, v63
	v_exp_f32 v62, v62
	s_waitcnt lgkmcnt(7)
	v_mfma_f32_32x32x16_bf16 v[96:111], v[150:153], v[120:123], v[96:111]
	ds_write_b128 v200, v[6:9]
	ds_read_b128 v[174:177], v190 offset:20128
	v_exp_f32 v63, v63
	v_add_f32 v188, v188, v60
	v_add_f32 v188, v188, v61
	v_cvt_pk_bf16_f32 v54, v60, v61
	v_add_f32 v188, v188, v62
	v_add_f32 v188, v188, v63
	v_cvt_pk_bf16_f32 v55, v62, v63
	v_max3_f32 v211, v211, v64, v65
	s_waitcnt lgkmcnt(8)
	v_mfma_f32_32x32x16_bf16 v[80:95], v[154:157], v[124:127], v[80:95]
	ds_read_b64_tr_b16 v[146:147], v191 offset:0
	ds_read_b64_tr_b16 v[148:149], v191 offset:1024
	v_exp_f32 v64, v64
	v_exp_f32 v65, v65
	v_max3_f32 v211, v211, v66, v67
	v_exp_f32 v66, v66
	v_exp_f32 v67, v67
	v_add_f32 v188, v188, v64
	v_add_f32 v188, v188, v65
	v_cvt_pk_bf16_f32 v64, v64, v65
	s_waitcnt lgkmcnt(8)
	v_mfma_f32_32x32x16_bf16 v[96:111], v[158:161], v[124:127], v[96:111]
	ds_write_b128 v200, v[136:139] offset:8192
	ds_read_b64_tr_b16 v[150:151], v192 offset:0
	ds_read_b64_tr_b16 v[152:153], v192 offset:1024
	v_max3_f32 v211, v211, v68, v69
	v_exp_f32 v68, v68
	v_exp_f32 v69, v69
	v_add_f32 v188, v188, v66
	v_add_f32 v188, v188, v67
	v_cvt_pk_bf16_f32 v65, v66, v67
	v_max3_f32 v211, v211, v70, v71
	v_exp_f32 v70, v70
	s_waitcnt lgkmcnt(10)
	v_mfma_f32_32x32x16_bf16 v[80:95], v[162:165], v[128:131], v[80:95]
	ds_read_b64_tr_b16 v[154:155], v191 offset:2048
	ds_read_b64_tr_b16 v[156:157], v191 offset:3072
	v_exp_f32 v71, v71
	v_add_f32 v188, v188, v68
	v_add_f32 v188, v188, v69
	v_cvt_pk_bf16_f32 v66, v68, v69
	v_max3_f32 v211, v211, v72, v73
	v_exp_f32 v72, v72
	v_exp_f32 v73, v73
	v_add_f32 v188, v188, v70
	s_waitcnt lgkmcnt(10)
	v_mfma_f32_32x32x16_bf16 v[96:111], v[166:169], v[128:131], v[96:111]
	ds_write_b128 v201, v[140:143]
	ds_read_b64_tr_b16 v[158:159], v192 offset:2048
	ds_read_b64_tr_b16 v[160:161], v192 offset:3072
	v_add_f32 v188, v188, v71
	v_cvt_pk_bf16_f32 v67, v70, v71
	v_max3_f32 v211, v211, v74, v75
	v_exp_f32 v74, v74
	v_exp_f32 v75, v75
	v_add_f32 v188, v188, v72
	v_add_f32 v188, v188, v73
	v_cvt_pk_bf16_f32 v68, v72, v73
	s_waitcnt lgkmcnt(12)
	v_mfma_f32_32x32x16_bf16 v[80:95], v[170:173], v[132:135], v[80:95]
	ds_read_b64_tr_b16 v[162:163], v191 offset:4096
	ds_read_b64_tr_b16 v[164:165], v191 offset:5120
	v_max3_f32 v211, v211, v76, v77
	v_exp_f32 v76, v76
	v_exp_f32 v77, v77
	v_add_f32 v188, v188, v74
	v_add_f32 v188, v188, v75
	v_cvt_pk_bf16_f32 v69, v74, v75
	v_max3_f32 v211, v211, v78, v79
	v_exp_f32 v78, v78
	s_waitcnt lgkmcnt(12)
	v_mfma_f32_32x32x16_bf16 v[96:111], v[174:177], v[132:135], v[96:111]
	ds_read_b64_tr_b16 v[166:167], v192 offset:4096
	ds_read_b64_tr_b16 v[168:169], v192 offset:5120
	v_exp_f32 v79, v79
	v_add_f32 v188, v188, v76
	v_add_f32 v188, v188, v77
	v_cvt_pk_bf16_f32 v70, v76, v77
	v_add_f32 v188, v188, v78
	v_add_f32 v188, v188, v79
	v_cvt_pk_bf16_f32 v71, v78, v79
	v_add_f32 v206, v206, v188
	s_cmp_eq_u32 s13, 2
	s_cselect_b32 s8, 0x1f800, 0
	s_sub_u32 s8, 0xa800, s8
	s_add_u32 s13, s13, 1
	s_cmp_eq_u32 s13, 3
	s_cselect_b32 s13, 0, s13
	s_waitcnt lgkmcnt(0)
	s_add_u32 s9, s26, 2
	s_cmp_lt_u32 s9, s30
	s_cbranch_scc0 .Lat0_mid1
; template <int TYPE>
; __device__ __forceinline__ void attn_item(const Ctx& a, int b, int h, int qt, LAS unsigned char* lds) {
;     ...
;         if (kp + 1 < npair) AT_LOAD(kp + 1);
	global_load_dwordx4 v[2:5], v184, s[52:53]
	global_load_dwordx4 v[6:9], v184, s[52:53] offset:128
	global_load_dwordx4 v[10:13], v185, s[52:53]
	global_load_dwordx4 v[136:139], v185, s[52:53] offset:128
	global_load_dwordx4 v[140:143], v186, s[54:55]
	s_add_u32 s52, s52, 0x70000
	s_addc_u32 s53, s53, 0
	s_add_u32 s54, s54, 0x10000
	s_addc_u32 s55, s55, 0

; __device__ __forceinline__ unsigned cvt_pk(float lo, float hi) { f32x2_t v = {lo, hi}; bf16x2_t b = __builtin_convertvector(v, bf16x2_t); return __builtin_bit_cast(unsigned, b); }
; __device__ __forceinline__ int fresh_tid() { int t; asm volatile("v_mov_b32 %0, %1" : "=v"(t) : "v"(threadIdx.x)); return t; }
; template <int TYPE>
; __device__ __forceinline__ void attn_item(const Ctx& a, int b, int h, int qt, LAS unsigned char* lds) {
;     ...
;     const int tid = fresh_tid(), lane = tid & 63, wv = tid >> 6, l32 = lane & 31, hb = lane >> 5;
;     const bf16_t* mr = (const bf16_t*)(a.ws + B_MLA); const bf16_t* pa = (const bf16_t*)(a.ws + B_PROJ); const bf16_t* kro = (const bf16_t*)(a.ws + B_KROPE);
;     bf16_t* br = (bf16_t*)(a.ws + B_BRANCH);
;     const int qrow = qt * 256 + wv * 32 + l32;
;     bf16x8 Q[NKK];
;     {
;         const bf16_t* qp = TYPE == 0 ? mr + (size_t)qrow * MR + h * 96 : pa + (size_t)qrow * PA + C_MQ + h * 64;
; #pragma unroll
;         for (int kk = 0; kk < NKK; ++kk) Q[kk] = *(const bf16x8*)(qp + kk * 16 + hb * 8);
;     }
;     unsigned qmask = 0xffffffffu;
;     if (TYPE == 1) qmask = ((const unsigned*)(a.ws + WS_MASK))[(size_t)h * SEQ + qrow];
;     f32x16 oacc[2];
; #pragma unroll
;     for (int db = 0; db < 2; ++db)
; #pragma unroll
;         for (int r = 0; r < 16; ++r) oacc[db][r] = 0.f;
;     float mrun = 0.f, lrun = 0.f;
;     const int npair = (qt + 1) * 2;
;     u32x4 kreg[NKC], vreg[2];
;     ...
;     AT_LOAD(0); AT_STORE(0);
;     __syncthreads();
;     ...
;     lrun += __shfl_xor(lrun, 32);
;     const float inv = 1.f / lrun;
;     bf16_t* op = br + ((size_t)b * SEQ + qrow) * BR + (TYPE == 0 ? 0 : 1024) + h * 64;
; #pragma unroll
;     for (int db = 0; db < 2; ++db)
; #pragma unroll
;         for (int g = 0; g < 4; ++g) {
;             u32x2 w; w[0] = cvt_pk(oacc[db][g * 4 + 0] * inv, oacc[db][g * 4 + 1] * inv); w[1] = cvt_pk(oacc[db][g * 4 + 2] * inv, oacc[db][g * 4 + 3] * inv);
;             *(u32x2*)(op + db * 32 + g * 8 + hb * 4) = w;
;         }
.Lat0_epi:
	v_mov_b32 v1, v206
	s_nop 1
	v_permlane32_swap_b32 v1, v206
	v_add_f32 v1, v1, v206
	v_div_scale_f32 v4, s[0:1], v1, v1, 1.0
	v_rcp_f32 v5, v4
	v_div_scale_f32 v6, vcc, 1.0, v1, 1.0
	v_fma_f32 v7, -v4, v5, 1.0
	v_fmac_f32 v5, v7, v5
	v_mul_f32 v7, v6, v5
	v_fma_f32 v8, -v4, v7, v6
	v_fmac_f32 v7, v8, v5
	v_fma_f32 v4, -v4, v7, v6
	v_div_fmas_f32 v4, v4, v5, v7
	v_div_fixup_f32 v4, v4, v1, 1.0
	v_readlane_b32 s8, v255, 7
	s_mul_i32 s8, s8, 0xc00
	s_lshl_b32 s9, s50, 7
	s_add_u32 s8, s8, s9
	s_add_u32 s56, s18, s8
	s_addc_u32 s57, s19, 0
	s_movk_i32 s8, 0xc00
	v_mul_lo_u32 v181, v144, s8
	v_lshrrev_b32 v15, 5, v195
	v_lshl_add_u32 v181, v15, 3, v181
	v_mul_f32 v6, v4, v16
	v_mul_f32 v7, v4, v17
	v_mul_f32 v8, v4, v18
	v_mul_f32 v9, v4, v19
	v_cvt_pk_bf16_f32 v10, v6, v7
	v_cvt_pk_bf16_f32 v11, v8, v9
	global_store_dwordx2 v181, v[10:11], s[56:57] offset:0
	v_mul_f32 v6, v4, v20
	v_mul_f32 v7, v4, v21
	v_mul_f32 v8, v4, v22
	v_mul_f32 v9, v4, v23
	v_cvt_pk_bf16_f32 v12, v6, v7
	v_cvt_pk_bf16_f32 v13, v8, v9
	global_store_dwordx2 v181, v[12:13], s[56:57] offset:16
	v_mul_f32 v6, v4, v24
	v_mul_f32 v7, v4, v25
	v_mul_f32 v8, v4, v26
	v_mul_f32 v9, v4, v27
	v_cvt_pk_bf16_f32 v10, v6, v7
	v_cvt_pk_bf16_f32 v11, v8, v9
	global_store_dwordx2 v181, v[10:11], s[56:57] offset:32
	v_mul_f32 v6, v4, v28
	v_mul_f32 v7, v4, v29
	v_mul_f32 v8, v4, v30
	v_mul_f32 v9, v4, v31
	v_cvt_pk_bf16_f32 v12, v6, v7
	v_cvt_pk_bf16_f32 v13, v8, v9
	global_store_dwordx2 v181, v[12:13], s[56:57] offset:48
	v_mul_f32 v6, v4, v32
	v_mul_f32 v7, v4, v33
	v_mul_f32 v8, v4, v34
	v_mul_f32 v9, v4, v35
	v_cvt_pk_bf16_f32 v10, v6, v7
	v_cvt_pk_bf16_f32 v11, v8, v9
	global_store_dwordx2 v181, v[10:11], s[56:57] offset:64
	v_mul_f32 v6, v4, v36
	v_mul_f32 v7, v4, v37
	v_mul_f32 v8, v4, v38
	v_mul_f32 v9, v4, v39
	v_cvt_pk_bf16_f32 v12, v6, v7
	v_cvt_pk_bf16_f32 v13, v8, v9
	global_store_dwordx2 v181, v[12:13], s[56:57] offset:80
	v_mul_f32 v6, v4, v40
	v_mul_f32 v7, v4, v41
	v_mul_f32 v8, v4, v42
	v_mul_f32 v9, v4, v43
	v_cvt_pk_bf16_f32 v10, v6, v7
	v_cvt_pk_bf16_f32 v11, v8, v9
	global_store_dwordx2 v181, v[10:11], s[56:57] offset:96
	v_mul_f32 v6, v4, v44
	v_mul_f32 v7, v4, v45
	v_mul_f32 v8, v4, v46
	v_mul_f32 v9, v4, v47
	v_cvt_pk_bf16_f32 v12, v6, v7
	v_cvt_pk_bf16_f32 v13, v8, v9
	global_store_dwordx2 v181, v[12:13], s[56:57] offset:112
	s_setprio 0
	s_barrier
	s_mov_b64 s[0:1], -1
	s_branch .LBB0_296
.Lat1_entry:
	s_lshr_b32 s47, s12, 4
	s_sub_u32 s47, 31, s47
	s_and_b32 s50, s12, 7
	v_lshrrev_b32 v1, 6, v179
	s_add_u32 s30, s47, 1
	s_lshl_b32 s30, s30, 1
	v_readfirstlane_b32 s51, v1
	v_and_b32 v14, 31, v195
	v_lshrrev_b32 v15, 5, v195
	s_lshl_b32 s8, s47, 8
	s_lshl_b32 s9, s51, 5
	s_add_u32 s8, s8, s9
	v_add_u32 v144, s8, v14
	v_add_u32 v208, s9, v14
	v_lshlrev_b32 v181, 2, v15
	v_sub_u32 v208, v208, v181
	s_lshl_b32 s9, s50, 7
	s_add_u32 s56, s70, 0x1350
	s_addc_u32 s57, s71, 0
	s_add_u32 s56, s56, s9
	s_addc_u32 s57, s57, 0
	v_lshlrev_b32 v181, 13, v144
	v_lshl_add_u32 v181, v15, 4, v181
	global_load_dwordx4 v[112:115], v181, s[56:57] offset:0
	global_load_dwordx4 v[116:119], v181, s[56:57] offset:32
	global_load_dwordx4 v[120:123], v181, s[56:57] offset:64
	global_load_dwordx4 v[124:127], v181, s[56:57] offset:96
	s_lshl_b32 s9, s50, 15
	s_add_u32 s56, s16, 0x58b0000
	s_addc_u32 s57, s17, 0
	s_add_u32 s56, s56, s9
	s_addc_u32 s57, s57, 0
	v_lshlrev_b32 v212, 2, v144
	global_load_dword v209, v212, s[56:57]
	v_lshrrev_b32 v181, 3, v179
	v_and_b32 v212, 7, v179
	s_lshl_b32 s9, s50, 7
	s_add_u32 s52, s70, 0x1750
	s_addc_u32 s53, s71, 0
	s_add_u32 s52, s52, s9
	s_addc_u32 s53, s53, 0
	v_lshlrev_b32 v184, 13, v181
	v_lshl_add_u32 v184, v212, 4, v184
	v_add_u32 v185, 0x80000, v184
	v_mul_u32_u24 v190, 144, v14
	v_lshl_add_u32 v190, v15, 4, v190
	v_mul_u32_u24 v193, 144, v181
	v_lshl_add_u32 v193, v212, 4, v193
	v_and_b32 v1, 2, v181
	v_lshlrev_b32 v1, 5, v1
	v_lshlrev_b32 v188, 4, v212
	v_xor_b32 v1, v1, v188
	v_lshl_add_u32 v200, v181, 7, v1
	v_add_u32 v200, 18432, v200
	v_bfe_u32 v1, v195, 2, 2
	v_lshlrev_b32 v191, 7, v1
	v_bfe_u32 v1, v195, 3, 1
	v_lshl_add_u32 v191, v1, 6, v191
	v_bfe_u32 v1, v195, 4, 1
	v_lshl_add_u32 v191, v1, 5, v191
	v_and_b32 v1, 3, v195
	v_lshl_add_u32 v191, v1, 3, v191
	v_lshl_add_u32 v191, v15, 9, v191
	v_add_u32 v191, 18432, v191
	v_xor_b32 v192, 64, v191
	global_load_dwordx4 v[2:5], v184, s[52:53]
	global_load_dwordx4 v[6:9], v184, s[52:53] offset:1024
	global_load_dwordx4 v[10:13], v185, s[52:53]
	global_load_dwordx4 v[136:139], v185, s[52:53] offset:1024
	s_add_u32 s52, s52, 0x100000
	s_addc_u32 s53, s53, 0
	v_mov_b32 v16, 0
	v_mov_b32 v17, 0
	v_mov_b32 v18, 0
	v_mov_b32 v19, 0
	v_mov_b32 v20, 0
	v_mov_b32 v21, 0
	v_mov_b32 v22, 0
	v_mov_b32 v23, 0
	v_mov_b32 v24, 0
	v_mov_b32 v25, 0
	v_mov_b32 v26, 0
	v_mov_b32 v27, 0
	v_mov_b32 v28, 0
	v_mov_b32 v29, 0
	v_mov_b32 v30, 0
	v_mov_b32 v31, 0
	v_mov_b32 v32, 0
	v_mov_b32 v33, 0
	v_mov_b32 v34, 0
	v_mov_b32 v35, 0
	v_mov_b32 v36, 0
	v_mov_b32 v37, 0
	v_mov_b32 v38, 0
	v_mov_b32 v39, 0
	v_mov_b32 v40, 0
	v_mov_b32 v41, 0
	v_mov_b32 v42, 0
	v_mov_b32 v43, 0
	v_mov_b32 v44, 0
	v_mov_b32 v45, 0
	v_mov_b32 v46, 0
	v_mov_b32 v47, 0
	v_mov_b32 v205, 0
	v_mov_b32 v206, 0
	v_mov_b32 v207, 0x41000000
	s_mov_b64 s[36:37], 0
	s_mov_b32 s26, 0
	s_waitcnt vmcnt(0)
	ds_write_b128 v193, v[2:5]
	ds_write_b128 v193, v[10:13] offset:9216
	ds_write_b128 v200, v[6:9]
	ds_write_b128 v200, v[136:139] offset:8192
	s_waitcnt lgkmcnt(0)
	global_load_dwordx4 v[2:5], v184, s[52:53]
	global_load_dwordx4 v[6:9], v184, s[52:53] offset:1024
	global_load_dwordx4 v[10:13], v185, s[52:53]
	global_load_dwordx4 v[136:139], v185, s[52:53] offset:1024
	s_add_u32 s52, s52, 0x100000
	s_addc_u32 s53, s53, 0
	s_mov_b32 s8, 0x8800
	v_add_u32 v193, s8, v193
	v_add_u32 v200, s8, v200
	s_mov_b32 s12, 0
	s_mov_b32 s13, 1
	s_waitcnt lgkmcnt(0)
	s_barrier
	s_cmp_ge_u32 s51, 4
	s_cbranch_scc0 .Lat1_prio_done
	s_setprio 1
; template <int TYPE>
; __device__ __forceinline__ void attn_item(const Ctx& a, int b, int h, int qt, LAS unsigned char* lds) {
;     ...
;         for (int kk = 0; kk < NKK; ++kk)
; #pragma unroll
;             for (int sub = 0; sub < 2; ++sub)
;                 if (act[sub]) {
; #pragma unroll
;                     for (int kb = 0; kb < 2; ++kb) {
;                         bf16x8 ka = *(const LAS bf16x8*)(Kt + (sub * 64 + kb * 32 + l32) * KLD + kk * 16 + hb * 8);
;                         s[sub][kb] = __builtin_amdgcn_mfma_f32_32x32x16_bf16(ka, Q[kk], s[sub][kb], 0, 0, 0);
;                     }
;                 }
; #pragma unroll
;         for (int sub = 0; sub < 2; ++sub) {
;             if (!act[sub]) continue;
;             const int kt = kp * 2 + sub, kloc = kt - qt * 4;
;             if (kloc >= 0) {
; #pragma unroll
;                 for (int kb = 0; kb < 2; ++kb)
; #pragma unroll
;                     for (int r = 0; r < 16; ++r) { int kabs = kt * 64 + kb * 32 + (r >> 2) * 8 + hb * 4 + (r & 3); if (kabs > qrow) s[sub][kb][r] = -1e30f; }
;             } else if (TYPE == 1) {
;                 if (!((qmask >> (kt >> 2)) & 1u)) {
; #pragma unroll
;                     for (int kb = 0; kb < 2; ++kb)
; #pragma unroll
;                         for (int r = 0; r < 16; ++r) s[sub][kb][r] = -1e30f;
;                 }
;             }
;             float mx = -1e30f;
; #pragma unroll
;             for (int kb = 0; kb < 2; ++kb)
; #pragma unroll
;                 for (int r = 0; r < 16; ++r) mx = fmaxf(mx, s[sub][kb][r]);
;             mx = fmaxf(mx, __shfl_xor(mx, 32));
;             const float delta = mrun - mref;
;             const bool bump = (mx - delta) > 8.f;
;             const bool rare = __builtin_amdgcn_ballot_w64(bump || delta != 0.f) != 0ull;
;             float fpost = 1.f;
;             if (rare) {
;                 const float mnew = bump ? mref + mx : mrun;
;                 const float pre = __builtin_amdgcn_exp2f(delta);
;                 fpost = __builtin_amdgcn_exp2f(mref - mnew);
;                 mrun = mnew;
;                 lrun *= pre;
; #pragma unroll
;                 for (int db = 0; db < 2; ++db)
; #pragma unroll
;                     for (int r = 0; r < 16; ++r) oacc[db][r] *= pre;
;             }
;             float ps = 0.f;
; #pragma unroll
;             for (int kb = 0; kb < 2; ++kb)
; #pragma unroll
.Lat1_prio_done:
.Lat1_loop:
	s_add_u32 s8, s26, 2
	s_cmp_ge_u32 s8, s30
	s_cselect_b32 s57, 1, 0
	s_lshr_b32 s8, s26, 1
	v_lshrrev_b32 v1, s8, v209
	v_and_b32 v1, 1, v1
	v_sub_u32 v210, 0, v1
	v_cmp_ne_u32_e64 s[38:39], 0, v1
	s_cmp_eq_u32 s57, 1
	s_cbranch_scc1 .Lat1_gen
	s_cmp_eq_u64 s[38:39], 0
	s_cbranch_scc1 .Lat1_skip
	s_cmp_lg_u64 s[36:37], 0
	s_cbranch_scc1 .Lat1_gen
	v_mov_b32 v211, v0
	ds_read_b128 v[146:149], v190 offset:0
	ds_read_b128 v[150:153], v190 offset:4608
	ds_read_b128 v[154:157], v190 offset:32
	ds_read_b128 v[158:161], v190 offset:4640
	ds_read_b128 v[162:165], v190 offset:64
	ds_read_b128 v[166:169], v190 offset:4672
	s_waitcnt lgkmcnt(5)
	v_mfma_f32_32x32x16_bf16 v[48:63], v[146:149], v[112:115], 0
	ds_read_b128 v[170:173], v190 offset:96
	s_waitcnt lgkmcnt(5)
	v_mfma_f32_32x32x16_bf16 v[64:79], v[150:153], v[112:115], 0
	ds_read_b128 v[174:177], v190 offset:4704
	s_waitcnt lgkmcnt(5)
	v_mfma_f32_32x32x16_bf16 v[48:63], v[154:157], v[116:119], v[48:63]
	ds_read_b128 v[146:149], v190 offset:9216
	s_waitcnt lgkmcnt(5)
	v_mfma_f32_32x32x16_bf16 v[64:79], v[158:161], v[116:119], v[64:79]
	ds_read_b128 v[150:153], v190 offset:13824
	s_waitcnt lgkmcnt(5)
	v_mfma_f32_32x32x16_bf16 v[48:63], v[162:165], v[120:123], v[48:63]
	ds_read_b128 v[154:157], v190 offset:9248
	s_waitcnt lgkmcnt(5)
	v_mfma_f32_32x32x16_bf16 v[64:79], v[166:169], v[120:123], v[64:79]
	ds_read_b128 v[158:161], v190 offset:13856
	s_waitcnt lgkmcnt(5)
	v_mfma_f32_32x32x16_bf16 v[48:63], v[170:173], v[124:127], v[48:63]
	ds_read_b128 v[162:165], v190 offset:9280
	s_waitcnt lgkmcnt(5)
	v_mfma_f32_32x32x16_bf16 v[64:79], v[174:177], v[124:127], v[64:79]
	ds_read_b128 v[166:169], v190 offset:13888
	s_waitcnt vmcnt(0)
	s_waitcnt lgkmcnt(5)
	v_mfma_f32_32x32x16_bf16 v[80:95], v[146:149], v[112:115], 0
	ds_read_b128 v[170:173], v190 offset:9312
	s_nop 3
	v_max3_f32 v211, v211, v48, v49
	v_exp_f32 v48, v48
	v_exp_f32 v49, v49
	v_max3_f32 v211, v211, v50, v51
	v_exp_f32 v50, v50
	v_exp_f32 v51, v51
	v_add_f32 v188, v48, v49
	v_cvt_pk_bf16_f32 v48, v48, v49
	v_and_b32 v48, v48, v210
	v_max3_f32 v211, v211, v52, v53
	v_exp_f32 v52, v52
	v_exp_f32 v53, v53
	v_add_f32 v188, v188, v50
	v_add_f32 v188, v188, v51
	s_waitcnt lgkmcnt(5)
	v_mfma_f32_32x32x16_bf16 v[96:111], v[150:153], v[112:115], 0
	ds_write_b128 v193, v[2:5]
	ds_read_b128 v[174:177], v190 offset:13920
	v_cvt_pk_bf16_f32 v49, v50, v51
	v_and_b32 v49, v49, v210
	v_max3_f32 v211, v211, v54, v55
	v_exp_f32 v54, v54
	v_exp_f32 v55, v55
	v_add_f32 v188, v188, v52
	v_add_f32 v188, v188, v53
	v_cvt_pk_bf16_f32 v50, v52, v53
	v_and_b32 v50, v50, v210
	v_max3_f32 v211, v211, v56, v57
	v_exp_f32 v56, v56
	v_exp_f32 v57, v57
	v_add_f32 v188, v188, v54
	v_add_f32 v188, v188, v55
	s_waitcnt lgkmcnt(6)
	v_mfma_f32_32x32x16_bf16 v[80:95], v[154:157], v[116:119], v[80:95]
	ds_read_b64_tr_b16 v[146:147], v191 offset:0
	ds_read_b64_tr_b16 v[148:149], v191 offset:1024
	v_cvt_pk_bf16_f32 v51, v54, v55
	v_and_b32 v51, v51, v210
	v_max3_f32 v211, v211, v58, v59
	v_exp_f32 v58, v58
	v_exp_f32 v59, v59
	v_add_f32 v188, v188, v56
	v_add_f32 v188, v188, v57
	v_cvt_pk_bf16_f32 v52, v56, v57
	v_and_b32 v52, v52, v210
	v_max3_f32 v211, v211, v60, v61
	v_exp_f32 v60, v60
	v_exp_f32 v61, v61
	v_add_f32 v188, v188, v58
	v_add_f32 v188, v188, v59
	s_waitcnt lgkmcnt(7)
	v_mfma_f32_32x32x16_bf16 v[96:111], v[158:161], v[116:119], v[96:111]
	ds_write_b128 v193, v[10:13] offset:9216
	ds_read_b64_tr_b16 v[150:151], v192 offset:0
	ds_read_b64_tr_b16 v[152:153], v192 offset:1024
	v_cvt_pk_bf16_f32 v53, v58, v59
	v_and_b32 v53, v53, v210
	v_max3_f32 v211, v211, v62, v63
	v_exp_f32 v62, v62
	v_exp_f32 v63, v63
	v_add_f32 v188, v188, v60
	v_add_f32 v188, v188, v61
	v_cvt_pk_bf16_f32 v54, v60, v61
	v_and_b32 v54, v54, v210
	v_add_f32 v188, v188, v62
	v_add_f32 v188, v188, v63
	v_cvt_pk_bf16_f32 v55, v62, v63
	v_and_b32 v55, v55, v210
	v_max3_f32 v211, v211, v64, v65
	s_waitcnt lgkmcnt(9)
	v_mfma_f32_32x32x16_bf16 v[80:95], v[162:165], v[120:123], v[80:95]
	ds_read_b64_tr_b16 v[154:155], v191 offset:2048
	ds_read_b64_tr_b16 v[156:157], v191 offset:3072
	v_exp_f32 v64, v64
	v_exp_f32 v65, v65
	v_max3_f32 v211, v211, v66, v67
	v_exp_f32 v66, v66
	v_exp_f32 v67, v67
	v_add_f32 v188, v188, v64
	v_add_f32 v188, v188, v65
	v_cvt_pk_bf16_f32 v64, v64, v65
	v_and_b32 v64, v64, v210
	v_max3_f32 v211, v211, v68, v69
	v_exp_f32 v68, v68
	v_exp_f32 v69, v69
	v_add_f32 v188, v188, v66
	v_add_f32 v188, v188, v67
	s_waitcnt lgkmcnt(10)
	v_mfma_f32_32x32x16_bf16 v[96:111], v[166:169], v[120:123], v[96:111]
	ds_write_b128 v200, v[6:9]
	ds_read_b64_tr_b16 v[158:159], v192 offset:2048
	ds_read_b64_tr_b16 v[160:161], v192 offset:3072
	v_cvt_pk_bf16_f32 v65, v66, v67
	v_and_b32 v65, v65, v210
	v_max3_f32 v211, v211, v70, v71
	v_exp_f32 v70, v70
	v_exp_f32 v71, v71
	v_add_f32 v188, v188, v68
	v_add_f32 v188, v188, v69
	v_cvt_pk_bf16_f32 v66, v68, v69
	v_and_b32 v66, v66, v210
	v_max3_f32 v211, v211, v72, v73
	v_exp_f32 v72, v72
	v_exp_f32 v73, v73
	v_add_f32 v188, v188, v70
	v_add_f32 v188, v188, v71
	s_waitcnt lgkmcnt(12)
	v_mfma_f32_32x32x16_bf16 v[80:95], v[170:173], v[124:127], v[80:95]
	ds_read_b64_tr_b16 v[162:163], v191 offset:4096
	ds_read_b64_tr_b16 v[164:165], v191 offset:5120
	v_cvt_pk_bf16_f32 v67, v70, v71
	v_and_b32 v67, v67, v210
	v_max3_f32 v211, v211, v74, v75
	v_exp_f32 v74, v74
	v_exp_f32 v75, v75
	v_add_f32 v188, v188, v72
	v_add_f32 v188, v188, v73
	v_cvt_pk_bf16_f32 v68, v72, v73
	v_and_b32 v68, v68, v210
	v_max3_f32 v211, v211, v76, v77
	v_exp_f32 v76, v76
	v_exp_f32 v77, v77
	v_add_f32 v188, v188, v74
	v_add_f32 v188, v188, v75
	s_waitcnt lgkmcnt(12)
	v_mfma_f32_32x32x16_bf16 v[96:111], v[174:177], v[124:127], v[96:111]
	ds_write_b128 v200, v[136:139] offset:8192
	ds_read_b64_tr_b16 v[166:167], v192 offset:4096
	ds_read_b64_tr_b16 v[168:169], v192 offset:5120
	v_cvt_pk_bf16_f32 v69, v74, v75
	v_and_b32 v69, v69, v210
	v_max3_f32 v211, v211, v78, v79
	v_exp_f32 v78, v78
	v_exp_f32 v79, v79
	v_add_f32 v188, v188, v76
	v_add_f32 v188, v188, v77
	v_cvt_pk_bf16_f32 v70, v76, v77
	v_and_b32 v70, v70, v210
	v_add_f32 v188, v188, v78
	v_add_f32 v188, v188, v79
	v_cvt_pk_bf16_f32 v71, v78, v79
	v_and_b32 v71, v71, v210
	v_and_b32 v188, v188, v210
	v_add_f32 v206, v206, v188
	s_cmp_eq_u32 s13, 2
	s_cselect_b32 s8, 0x19800, 0
	s_sub_u32 s8, 0x8800, s8
	s_add_u32 s13, s13, 1
	s_cmp_eq_u32 s13, 3
	s_cselect_b32 s13, 0, s13
	s_waitcnt lgkmcnt(0)
	s_add_u32 s9, s26, 2
	s_cmp_lt_u32 s9, s30
	s_cbranch_scc0 .Lat1_mid3
	global_load_dwordx4 v[2:5], v184, s[52:53]
	global_load_dwordx4 v[6:9], v184, s[52:53] offset:1024
	global_load_dwordx4 v[10:13], v185, s[52:53]
	global_load_dwordx4 v[136:139], v185, s[52:53] offset:1024
	s_add_u32 s52, s52, 0x100000
	s_addc_u32 s53, s53, 0

; __device__ __forceinline__ unsigned cvt_pk(float lo, float hi) { f32x2_t v = {lo, hi}; bf16x2_t b = __builtin_convertvector(v, bf16x2_t); return __builtin_bit_cast(unsigned, b); }
; template <int TYPE>
; __device__ __forceinline__ void attn_item(const Ctx& a, int b, int h, int qt, LAS unsigned char* lds) {
;     ...
;     lrun += __shfl_xor(lrun, 32);
;     const float inv = 1.f / lrun;
;     bf16_t* op = br + ((size_t)b * SEQ + qrow) * BR + (TYPE == 0 ? 0 : 1024) + h * 64;
; #pragma unroll
;     for (int db = 0; db < 2; ++db)
; #pragma unroll
;         for (int g = 0; g < 4; ++g) {
;             u32x2 w; w[0] = cvt_pk(oacc[db][g * 4 + 0] * inv, oacc[db][g * 4 + 1] * inv); w[1] = cvt_pk(oacc[db][g * 4 + 2] * inv, oacc[db][g * 4 + 3] * inv);
;             *(u32x2*)(op + db * 32 + g * 8 + hb * 4) = w;
;         }
.Lat1_epi:
	v_mov_b32 v1, v206
	s_nop 1
	v_permlane32_swap_b32 v1, v206
	v_add_f32 v1, v1, v206
	v_div_scale_f32 v4, s[0:1], v1, v1, 1.0
	v_rcp_f32 v5, v4
	v_div_scale_f32 v6, vcc, 1.0, v1, 1.0
	v_fma_f32 v7, -v4, v5, 1.0
	v_fmac_f32 v5, v7, v5
	v_mul_f32 v7, v6, v5
	v_fma_f32 v8, -v4, v7, v6
	v_fmac_f32 v7, v8, v5
	v_fma_f32 v4, -v4, v7, v6
	v_div_fmas_f32 v4, v4, v5, v7
	v_div_fixup_f32 v4, v4, v1, 1.0
	v_readlane_b32 s8, v255, 7
	s_mul_i32 s8, s8, 0xc00
	s_lshl_b32 s9, s50, 7
	s_add_u32 s8, s8, s9
	s_add_u32 s8, s8, 0x800
	s_add_u32 s56, s18, s8
	s_addc_u32 s57, s19, 0
	s_movk_i32 s8, 0xc00
	v_mul_lo_u32 v181, v144, s8
	v_lshrrev_b32 v15, 5, v195
	v_lshl_add_u32 v181, v15, 3, v181
	v_mul_f32 v6, v4, v16
	v_mul_f32 v7, v4, v17
	v_mul_f32 v8, v4, v18
	v_mul_f32 v9, v4, v19
	v_cvt_pk_bf16_f32 v10, v6, v7
	v_cvt_pk_bf16_f32 v11, v8, v9
	global_store_dwordx2 v181, v[10:11], s[56:57] offset:0
	v_mul_f32 v6, v4, v20
	v_mul_f32 v7, v4, v21
	v_mul_f32 v8, v4, v22
	v_mul_f32 v9, v4, v23
	v_cvt_pk_bf16_f32 v12, v6, v7
	v_cvt_pk_bf16_f32 v13, v8, v9
	global_store_dwordx2 v181, v[12:13], s[56:57] offset:16
	v_mul_f32 v6, v4, v24
	v_mul_f32 v7, v4, v25
	v_mul_f32 v8, v4, v26
	v_mul_f32 v9, v4, v27
	v_cvt_pk_bf16_f32 v10, v6, v7
	v_cvt_pk_bf16_f32 v11, v8, v9
	global_store_dwordx2 v181, v[10:11], s[56:57] offset:32
	v_mul_f32 v6, v4, v28
	v_mul_f32 v7, v4, v29
	v_mul_f32 v8, v4, v30
	v_mul_f32 v9, v4, v31
	v_cvt_pk_bf16_f32 v12, v6, v7
	v_cvt_pk_bf16_f32 v13, v8, v9
	global_store_dwordx2 v181, v[12:13], s[56:57] offset:48
	v_mul_f32 v6, v4, v32
	v_mul_f32 v7, v4, v33
	v_mul_f32 v8, v4, v34
	v_mul_f32 v9, v4, v35
	v_cvt_pk_bf16_f32 v10, v6, v7
	v_cvt_pk_bf16_f32 v11, v8, v9
	global_store_dwordx2 v181, v[10:11], s[56:57] offset:64
	v_mul_f32 v6, v4, v36
	v_mul_f32 v7, v4, v37
	v_mul_f32 v8, v4, v38
	v_mul_f32 v9, v4, v39
	v_cvt_pk_bf16_f32 v12, v6, v7
	v_cvt_pk_bf16_f32 v13, v8, v9
	global_store_dwordx2 v181, v[12:13], s[56:57] offset:80
	v_mul_f32 v6, v4, v40
	v_mul_f32 v7, v4, v41
	v_mul_f32 v8, v4, v42
	v_mul_f32 v9, v4, v43
	v_cvt_pk_bf16_f32 v10, v6, v7
	v_cvt_pk_bf16_f32 v11, v8, v9
	global_store_dwordx2 v181, v[10:11], s[56:57] offset:96
	v_mul_f32 v6, v4, v44
	v_mul_f32 v7, v4, v45
	v_mul_f32 v8, v4, v46
	v_mul_f32 v9, v4, v47
	v_cvt_pk_bf16_f32 v12, v6, v7
	v_cvt_pk_bf16_f32 v13, v8, v9
	global_store_dwordx2 v181, v[12:13], s[56:57] offset:112
	s_setprio 0
	s_barrier
	s_mov_b64 s[0:1], -1
